# static s_setprio 1 for waves 0-3 during attention phases (reset at phase end)
# baseline (speedup 1.0000x reference)
; __global__ void __launch_bounds__(512, 2) fwd_megakernel(Args args) {
;     ...
;         case K_ATTN: {
;             char* albs = (char*)lds_raw;
;             const bool need_ctx = (layer != 3);
;             const int gx = (G % 8 == 0) ? G / 8 : G, xcd = (G % 8 == 0) ? bx % 8 : 0, vl = (G % 8 == 0) ? bx / 8 : bx, nxc = (G % 8 == 0) ? 8 : 1;
;             if (mixer == 0) {
;                 const float C = 0.125f * 1.4426950408889634f, thr = 8.f / 0.125f;
;                 const float* lv = AIN(11) + mj * 256; const float* sg = AIN(12) + mj * 128;
;                 const float linit = (layer == 0) ? LAMINIT0 : LAMINIT3;
;                 const float sa = wave_sum(lv[lane] * lv[64 + lane]), sb = wave_sum(lv[128 + lane] * lv[192 + lane]);
;                 const float lam = __expf(sa) - __expf(sb) + linit;
;                 const int per_x = 1024 / nxc, nlat = (per_x - vl + gx - 1) / gx, nctx = need_ctx ? (64 - bx + G - 1) / G : 0;
;                 bf16x8 pfv0 = {}, pfv1 = {}, pfk0 = {}; const int nunits = 2 * (nlat + (nctx > 0 ? nctx : 0));
.LBB0_132:
	v_writelane_b32 v254, s44, 58
	s_cmp_gt_i32 s28, 3
	s_mov_b64 s[0:1], -1
	v_writelane_b32 v254, s45, 59
	v_writelane_b32 v254, s46, 60
	v_writelane_b32 v254, s47, 61
	v_writelane_b32 v254, s48, 62
	v_writelane_b32 v255, s50, 0
	v_writelane_b32 v254, s49, 63
	v_writelane_b32 v255, s51, 1
	s_movk_i32 s44, 0x1800
	s_mov_b32 s45, 0x4138aa3b
	s_mov_b64 s[42:43], 0x60000
	s_mov_b64 s[46:47], 0xc0000
	s_cbranch_scc0 .LBB0_250
	v_readfirstlane_b32 s0, v178
	s_nop 3
	s_lshr_b32 s0, s0, 6
	s_cmp_lt_u32 s0, 4
	s_cbranch_scc0 .Lattn_prio_done
	s_setprio 1
.Lattn_prio_done:
	s_ashr_i32 s2, s92, 31
	s_lshr_b32 s2, s2, 29
	s_add_i32 s2, s92, s2
	s_ashr_i32 s3, s2, 3
	s_and_b32 s2, s2, -8
	s_and_b32 s0, s93, 7
	s_ashr_i32 s1, s93, 3
	s_sub_i32 s2, s92, s2
	s_cmp_eq_u32 s0, 0
	s_waitcnt vmcnt(0)
	v_cndmask_b32_e64 v0, 0, 1, s[56:57]
	s_cselect_b32 s26, s1, s93
	s_cselect_b32 s18, s2, 0
	s_cselect_b32 s20, 3, 0
	s_cselect_b32 s19, s3, s92
	s_cmp_lg_u32 s30, 0
	v_cmp_ne_u32_e64 s[6:7], 1, v0
	s_cbranch_scc0 .LBB0_190
	s_and_b64 vcc, exec, s[6:7]
	s_mov_b32 s0, 0
	s_cbranch_vccnz .LBB0_136
	s_abs_i32 s0, s93
	v_cvt_f32_u32_e32 v0, s0
	s_sub_i32 s1, s93, s92
	s_add_i32 s2, s1, 63
	s_sub_i32 s1, 0xffffffc1, s1
	v_rcp_iflag_f32_e32 v0, v0
	s_xor_b32 s4, s2, s93
	s_sub_i32 s3, 0, s0
	s_max_i32 s1, s2, s1
	v_mul_f32_e32 v0, 0x4f7ffffe, v0
	v_cvt_u32_f32_e32 v0, v0
	s_ashr_i32 s2, s4, 31
	v_readfirstlane_b32 s4, v0
	s_mul_i32 s3, s3, s4
	s_mul_hi_u32 s3, s4, s3
	s_add_i32 s4, s4, s3
	s_mul_hi_u32 s3, s1, s4
	s_mul_i32 s4, s3, s0
	s_sub_i32 s1, s1, s4
	s_add_i32 s5, s3, 1
	s_sub_i32 s4, s1, s0
	s_cmp_ge_u32 s1, s0
	s_cselect_b32 s3, s5, s3
	s_cselect_b32 s1, s4, s1
	s_add_i32 s4, s3, 1
	s_cmp_ge_u32 s1, s0
	s_cselect_b32 s0, s4, s3
	s_xor_b32 s0, s0, s2
	s_sub_i32 s0, s0, s2
	s_max_i32 s0, s0, 0

; __global__ void __launch_bounds__(512, 2) fwd_megakernel(Args args) {
;     ...
;             } else {
;                 const float sc_ = 0.088388347648318440f; const float C = sc_ * 1.4426950408889634f, thr = 8.f / sc_;
;                 const int per_x = 1024 / nxc, nlat = (per_x - vl + gx - 1) / gx, nctx = need_ctx ? (64 - bx + G - 1) / G : 0;
;                 bf16x8 pg0 = {}, pg1 = {}, pg2 = {};
;                 for (int i = 0; i < nlat + (nctx > 0 ? nctx : 0); ++i) {
;                     int b, qh, kvh, seq; size_t qrow;
;                     if (i < nlat) { const int U = xcd * per_x + vl + i * gx, combo = U >> 6, k = U & 63; b = combo >> 1; kvh = combo & 1; qh = kvh * 4 + (k >> 4); qrow = (size_t)b * RPB + CTXL + (k & 15) * 256; seq = RPB; }
;                     else { const int U = bx + (i - nlat) * G; b = U >> 3; qh = U & 7; kvh = qh >> 2; qrow = (size_t)b * RPB; seq = CTXL; }
;                     const size_t krow = (size_t)b * RPB;
;     ...
;                     att::attn_unit<8, 1536, 1536, 1024>(R1 + qrow * 1536 + qh * 128, R1 + krow * 1536 + 1024 + kvh * 128, R1 + krow * 1536 + 1280 + kvh * 128,
;                                                         R2 + qrow * 1024 + qh * 128, seq, 0, C, thr, albs, 0, nullptr, 0.f, 0.f, pg0, pg1, pg2, 0, nullptr, -1, 0);
;     ...
;                 }
;             }
;         } break;
.LBB0_249:
	s_setprio 0
	s_mov_b64 s[0:1], 0
